# v30 + nt policy on attention phase loads and AO stores
# speedup vs baseline: 1.0253x; 1.0253x over previous
; __device__ __forceinline__ void attn_phase(LAS unsigned char* lds, const bf16* QKV, const float* sinks, bf16* AO, int G, int bid) {
;     ...
;     for (int u = bid; u < 256; u += G) {
;         const int hk = u & 3, nb = u >> 2;
;         {
;             v4u rk[4], rv[4];
; #pragma unroll
;             for (int i = 0; i < 4; ++i) { const int q = tid + 512 * i; const int t = nb * 128 - 128 + (q >> 3);
;                 if (t >= 0) { rk[i] = *(const v4u*)(QKV + (size_t)t * AIN + 2048 + hk * 64 + (q & 7) * 8); rv[i] = *(const v4u*)(QKV + (size_t)t * AIN + 2304 + hk * 64 + (q & 7) * 8); }
;                 else { rk[i] = (v4u){0u, 0u, 0u, 0u}; rv[i] = rk[i]; } }
.LBB0_86:
	s_lshl_b32 s0, s17, 5
	s_and_b32 s3, s0, 0xffffff80
	s_add_i32 s5, s3, 0xffffff80
	s_and_b32 s2, s17, 3
	v_add_u32_e32 v9, s5, v45
	s_lshl_b32 s4, s2, 6
	v_cmp_lt_i32_e32 vcc, -1, v9
	v_mov_b32_e32 v8, 0
	v_lshlrev_b32_e32 v42, 1, v2
	v_mov_b32_e32 v12, 0
	v_mov_b32_e32 v13, 0
	v_mov_b32_e32 v14, 0
	v_mov_b32_e32 v15, 0
	v_mov_b32_e32 v16, 0
	v_mov_b32_e32 v17, 0
	v_mov_b32_e32 v18, 0
	v_mov_b32_e32 v19, 0
	s_and_saveexec_b64 s[0:1], vcc
	s_movk_i32 s12, 0x1400
	s_cbranch_execz .LBB0_88
	v_mov_b64_e32 v[10:11], s[40:41]
	v_mad_u64_u32 v[10:11], s[10:11], v9, s12, v[10:11]
	s_lshl_b32 s20, s4, 1
	v_mov_b32_e32 v43, v1
	v_lshl_add_u64 v[10:11], v[10:11], 0, s[20:21]
	v_lshl_add_u64 v[10:11], v[10:11], 0, v[42:43]
	v_add_co_u32_e32 v10, vcc, 0x1000, v10
	s_nop 1
	v_addc_co_u32_e32 v11, vcc, 0, v11, vcc
	global_load_dwordx4 v[12:15], v[10:11], off nt
	global_load_dwordx4 v[16:19], v[10:11], off offset:512 nt
.LBB0_88:
	s_or_b64 exec, exec, s[0:1]
	v_add_u32_e32 v24, s5, v46
	v_cmp_lt_i32_e32 vcc, -1, v24
	v_mov_b32_e32 v9, 0
	v_mov_b32_e32 v10, 0
	v_mov_b32_e32 v11, 0
	v_mov_b32_e32 v20, 0
	v_mov_b32_e32 v21, 0
	v_mov_b32_e32 v22, 0
	v_mov_b32_e32 v23, 0
	s_and_saveexec_b64 s[0:1], vcc
	s_cbranch_execz .LBB0_90
	v_mov_b64_e32 v[8:9], s[40:41]
	v_mad_u64_u32 v[8:9], s[10:11], v24, s12, v[8:9]
	s_lshl_b32 s20, s4, 1
	v_mov_b32_e32 v43, v1
	v_lshl_add_u64 v[8:9], v[8:9], 0, s[20:21]
	v_lshl_add_u64 v[8:9], v[8:9], 0, v[42:43]
	v_add_co_u32_e32 v20, vcc, 0x1000, v8
	s_nop 1
	v_addc_co_u32_e32 v21, vcc, 0, v9, vcc
	global_load_dwordx4 v[8:11], v[20:21], off nt
	s_nop 0
	global_load_dwordx4 v[20:23], v[20:21], off offset:512 nt
.LBB0_90:
	s_or_b64 exec, exec, s[0:1]
	v_add_u32_e32 v25, s5, v47
	v_cmp_lt_i32_e32 vcc, -1, v25
	v_mov_b32_e32 v24, 0
	v_mov_b32_e32 v28, 0
	v_mov_b32_e32 v29, 0
	v_mov_b32_e32 v30, 0
	v_mov_b32_e32 v31, 0
	v_mov_b32_e32 v32, 0
	v_mov_b32_e32 v33, 0
	v_mov_b32_e32 v34, 0
	v_mov_b32_e32 v35, 0
	s_and_saveexec_b64 s[0:1], vcc
	s_cbranch_execz .LBB0_92
	v_mov_b64_e32 v[26:27], s[40:41]
	v_mad_u64_u32 v[26:27], s[10:11], v25, s12, v[26:27]
	s_lshl_b32 s20, s4, 1
	v_mov_b32_e32 v43, v1
	v_lshl_add_u64 v[26:27], v[26:27], 0, s[20:21]
	v_lshl_add_u64 v[26:27], v[26:27], 0, v[42:43]
	v_add_co_u32_e32 v26, vcc, 0x1000, v26
	s_nop 1
	v_addc_co_u32_e32 v27, vcc, 0, v27, vcc
	global_load_dwordx4 v[28:31], v[26:27], off nt
	global_load_dwordx4 v[32:35], v[26:27], off offset:512 nt
.LBB0_92:
	s_or_b64 exec, exec, s[0:1]
	v_add_u32_e32 v43, s5, v48
	v_cmp_lt_i32_e32 vcc, -1, v43
	v_mov_b32_e32 v25, 0
	v_mov_b32_e32 v26, 0
	v_mov_b32_e32 v27, 0
	v_mov_b32_e32 v36, 0
	v_mov_b32_e32 v37, 0
	v_mov_b32_e32 v38, 0
	v_mov_b32_e32 v39, 0
	s_and_saveexec_b64 s[0:1], vcc
	s_cbranch_execz .LBB0_94
	v_mov_b64_e32 v[24:25], s[40:41]
	v_mad_u64_u32 v[24:25], s[10:11], v43, s12, v[24:25]
	s_lshl_b32 s20, s4, 1
	v_mov_b32_e32 v43, v1
	v_lshl_add_u64 v[24:25], v[24:25], 0, s[20:21]
	v_lshl_add_u64 v[24:25], v[24:25], 0, v[42:43]
	v_add_co_u32_e32 v36, vcc, 0x1000, v24
	s_nop 1
	v_addc_co_u32_e32 v37, vcc, 0, v25, vcc
	global_load_dwordx4 v[24:27], v[36:37], off nt
	s_nop 0
	global_load_dwordx4 v[36:39], v[36:37], off offset:512 nt

; #define LBAR() do { asm volatile("s_waitcnt lgkmcnt(0)" ::: "memory"); __builtin_amdgcn_s_barrier(); asm volatile("" ::: "memory"); } while (0)
; __device__ __forceinline__ void attn_phase(LAS unsigned char* lds, const bf16* QKV, const float* sinks, bf16* AO, int G, int bid) {
;     ...
;         LBAR();
;         const int qfr = 128 + 16 * w + li;
;         const bf16* qrow = QKV + (size_t)(nb * 128 + 16 * w + li) * AIN + hk * 8 * 64 + 8 * g;
;         bf16x8 qn0 = *(const bf16x8*)(qrow), qn1 = *(const bf16x8*)(qrow + 32);
;         float sinkn = sinks[hk * 8];
;     ...
;                 for (int r = 0; r < 4; ++r) { const int j = 4 * g + r; const int dist = 128 + li - 16 * kt - j;
;                     bool valid = (kt == 0) ? (j > li) : ((kt == 8) ? (j <= li) : true);
;                     if (nb == 0) valid = valid && (16 * (w + kt) + j >= 128);
;                     s[r] = valid ? s[r] - slope * (float)dist : -INFINITY; mx = fmaxf(mx, s[r]); }
.LBB0_96:
	s_or_b64 exec, exec, s[0:1]
	s_and_b32 s0, s16, 0xffffff80
	v_add_u32_e32 v8, s0, v85
	v_ashrrev_i32_e32 v9, 31, v8
	s_and_b32 s1, s13, 3
	v_lshlrev_b64 v[8:9], 12, v[8:9]
	s_lshl_b32 s4, s1, 10
	v_or_b32_e32 v8, s4, v8
	v_writelane_b32 v254, s16, 55
	v_lshl_add_u64 v[24:25], v[40:41], 0, v[8:9]
	v_add_u32_e32 v8, s0, v86
	s_lshl_b32 s0, s1, 3
	v_writelane_b32 v254, s13, 56
	v_ashrrev_i32_e32 v9, 31, v8
	s_or_b32 s0, s0, 1
	v_lshlrev_b64 v[8:9], 12, v[8:9]
	v_writelane_b32 v253, s0, 13
	v_readlane_b32 s0, v254, 46
	v_or_b32_e32 v8, s4, v8
	s_add_i32 s3, s3, s0
	v_lshl_add_u64 v[26:27], v[40:41], 0, v[8:9]
	v_or_b32_e32 v10, s3, v3
	v_mov_b64_e32 v[8:9], s[40:41]
	v_mad_i64_i32 v[8:9], s[0:1], v10, s12, v[8:9]
	s_lshl_b32 s20, s2, 10
	v_lshl_add_u64 v[8:9], v[8:9], 0, s[20:21]
	s_lshl_b32 s0, s2, 5
	v_readlane_b32 s72, v252, 0
	s_waitcnt lgkmcnt(0)
	s_barrier
	v_lshl_add_u64 v[28:29], v[8:9], 0, v[0:1]
	v_readlane_b32 s84, v252, 12
	v_readlane_b32 s85, v252, 13
	v_mov_b32_e32 v16, s0
	global_load_dwordx4 v[12:15], v[28:29], off nt
	global_load_dwordx4 v[8:11], v[28:29], off offset:64 nt
	s_add_u32 s1, s84, s0
	v_writelane_b32 v253, s1, 15
	global_load_dword v32, v16, s[84:85]
	s_addc_u32 s1, s85, 0
	v_writelane_b32 v253, s1, 17
	v_writelane_b32 v254, s17, 57
	s_cmp_gt_u32 s17, 3
	v_cmp_lt_i32_e64 s[16:17], v219, v214
	v_readlane_b32 s0, v253, 28
	v_readlane_b32 s1, v253, 29
	v_cndmask_b32_e64 v16, v213, v219, s[16:17]
	v_cmp_lt_i32_e64 s[16:17], v220, v214
	v_lshlrev_b32_e32 v30, 2, v16
	s_cselect_b64 vcc, -1, 0
	v_cndmask_b32_e64 v16, v213, v220, s[16:17]
	v_lshlrev_b32_e32 v31, 2, v16
	v_cndmask_b32_e64 v16, 0, 1, s[0:1]
	v_readlane_b32 s0, v253, 30
	v_readlane_b32 s1, v253, 31
	v_readlane_b32 s82, v252, 10
	v_readlane_b32 s83, v252, 11
	v_cndmask_b32_e64 v17, 0, 1, s[0:1]
	v_cndmask_b32_e32 v16, v17, v16, vcc
	v_and_b32_e32 v16, 1, v16
	v_cmp_eq_u32_e64 s[0:1], 1, v16
	v_readlane_b32 s86, v252, 14
	v_readlane_b32 s87, v252, 15
	v_writelane_b32 v253, s0, 18
	v_readlane_b32 s74, v252, 2
	v_readlane_b32 s75, v252, 3
	v_writelane_b32 v253, s1, 19
	v_readlane_b32 s73, v252, 1
	v_readlane_b32 s0, v253, 32
	v_readlane_b32 s1, v253, 33
	v_readlane_b32 s76, v252, 4
	v_readlane_b32 s77, v252, 5
	v_cndmask_b32_e64 v16, 0, 1, s[0:1]
	v_readlane_b32 s0, v253, 34
	v_readlane_b32 s1, v253, 35
	v_readlane_b32 s78, v252, 6
	v_readlane_b32 s79, v252, 7
	v_cndmask_b32_e64 v17, 0, 1, s[0:1]
	v_cndmask_b32_e32 v16, v17, v16, vcc
	v_and_b32_e32 v16, 1, v16
	v_cmp_eq_u32_e64 s[0:1], 1, v16
	v_readlane_b32 s80, v252, 8
	v_readlane_b32 s81, v252, 9
	v_writelane_b32 v254, s0, 58
	s_mov_b32 s20, 0
	s_nop 0
	v_writelane_b32 v254, s1, 59
	v_readlane_b32 s0, v253, 36
	v_readlane_b32 s1, v253, 37
	s_nop 1
	v_cndmask_b32_e64 v16, 0, 1, s[0:1]
	v_readlane_b32 s0, v253, 38
	v_readlane_b32 s1, v253, 39
	s_nop 1
	v_cndmask_b32_e64 v17, 0, 1, s[0:1]
	v_cndmask_b32_e32 v16, v17, v16, vcc
	v_and_b32_e32 v16, 1, v16
	v_cmp_eq_u32_e64 s[0:1], 1, v16
	s_nop 1
	v_writelane_b32 v254, s0, 60
	s_nop 1
	v_writelane_b32 v254, s1, 61
	v_readlane_b32 s0, v253, 40
	v_readlane_b32 s1, v253, 41
	s_nop 1
	v_cndmask_b32_e64 v16, 0, 1, s[0:1]
	v_readlane_b32 s0, v253, 42
	v_readlane_b32 s1, v253, 43
	s_nop 1
	v_cndmask_b32_e64 v17, 0, 1, s[0:1]
	v_cndmask_b32_e32 v16, v17, v16, vcc
	v_and_b32_e32 v16, 1, v16
	v_cmp_eq_u32_e64 s[0:1], 1, v16
	s_nop 1
	v_writelane_b32 v254, s0, 62
	s_nop 1
	v_writelane_b32 v254, s1, 63
	v_readlane_b32 s0, v253, 44
	v_readlane_b32 s1, v253, 45
	s_or_b64 s[0:1], vcc, s[0:1]
	v_writelane_b32 v255, s0, 0
	v_readlane_b32 s82, v254, 30
	v_readlane_b32 s83, v254, 31
	v_writelane_b32 v255, s1, 1
	v_readlane_b32 s0, v253, 46
	v_readlane_b32 s1, v253, 47
	s_or_b64 s[0:1], vcc, s[0:1]
	v_writelane_b32 v255, s0, 2
	v_cndmask_b32_e64 v16, 0, 1, s[82:83]
	v_readlane_b32 s82, v254, 32
	v_writelane_b32 v255, s1, 3
	v_readlane_b32 s0, v253, 48
	v_readlane_b32 s1, v253, 49
	s_or_b64 s[0:1], vcc, s[0:1]
	v_writelane_b32 v255, s0, 4
	v_readlane_b32 s83, v254, 33
	v_readlane_b32 s84, v254, 34
	v_writelane_b32 v255, s1, 5
	v_readlane_b32 s0, v253, 50
	v_readlane_b32 s1, v253, 51
	s_or_b64 s[0:1], vcc, s[0:1]
	v_writelane_b32 v255, s0, 6
	v_cndmask_b32_e64 v17, 0, 1, s[82:83]
	v_cndmask_b32_e32 v16, v17, v16, vcc
	v_writelane_b32 v255, s1, 7
	v_readlane_b32 s0, v253, 52
	v_readlane_b32 s1, v253, 53
	s_or_b64 s[0:1], vcc, s[0:1]
	v_writelane_b32 v255, s0, 8
	v_and_b32_e32 v16, 1, v16
	v_readlane_b32 s85, v254, 35
	v_writelane_b32 v255, s1, 9
	v_readlane_b32 s0, v253, 54
	v_readlane_b32 s1, v253, 55
	s_or_b64 s[0:1], vcc, s[0:1]
	v_writelane_b32 v255, s0, 10
	v_cmp_eq_u32_e64 s[82:83], 1, v16
	v_cndmask_b32_e64 v16, 0, 1, s[84:85]
	v_readlane_b32 s84, v254, 36
	v_writelane_b32 v255, s1, 11
	v_readlane_b32 s0, v253, 56
	v_readlane_b32 s85, v254, 37
	v_readlane_b32 s1, v253, 57
	s_or_b64 s[0:1], vcc, s[0:1]
	v_cndmask_b32_e64 v17, 0, 1, s[84:85]
	v_cndmask_b32_e32 v16, v17, v16, vcc
	v_readlane_b32 s86, v254, 38
	v_writelane_b32 v255, s0, 12
	v_and_b32_e32 v16, 1, v16
	v_readlane_b32 s87, v254, 39
	v_writelane_b32 v255, s1, 13
	v_readlane_b32 s0, v253, 58
	v_cmp_eq_u32_e64 s[84:85], 1, v16
	v_cndmask_b32_e64 v16, 0, 1, s[86:87]
	v_readlane_b32 s86, v254, 40
	v_readlane_b32 s1, v253, 59
	v_readlane_b32 s87, v254, 41
	s_or_b64 s[38:39], vcc, s[0:1]
	v_readlane_b32 s0, v253, 60
	v_readlane_b32 s2, v254, 4
	v_cndmask_b32_e64 v17, 0, 1, s[86:87]
	v_readlane_b32 s1, v253, 61
	v_readlane_b32 s3, v254, 5
	v_cndmask_b32_e32 v16, v17, v16, vcc
	v_readlane_b32 s88, v254, 42
	s_or_b64 s[22:23], vcc, s[0:1]
	v_readlane_b32 s0, v253, 62
	s_or_b64 s[92:93], vcc, s[2:3]
	v_readlane_b32 s2, v254, 6
; #define LAS __attribute__((address_space(3)))
; #define MFMA16(a, b, c) __builtin_amdgcn_mfma_f32_16x16x32_bf16((a), (b), (c), 0, 0, 0)
; __device__ __forceinline__ void attn_phase(LAS unsigned char* lds, const bf16* QKV, const float* sinks, bf16* AO, int G, int bid) {
;     ...
;         for (int hg = 0; hg < 8; ++hg) {
;             const int hq = hk * 8 + hg;
;             const float slope = exp2f(-0.25f * (float)(hq + 1)); const float sink = sinkn;
;             const bf16x8 q0 = qn0, q1 = qn1;
;             { const int hn = (hg < 7) ? hg + 1 : 7; qn0 = *(const bf16x8*)(qrow + hn * 64); qn1 = *(const bf16x8*)(qrow + hn * 64 + 32); sinkn = sinks[hk * 8 + hn]; }
;             f32x4 sc[10]; float mx = sink;
; #pragma unroll
;             for (int kh = 0; kh < 2; ++kh) {
;             bf16x8 ka_[5], kb_[5];
; #pragma unroll
;             for (int k5 = 0; k5 < 5 - kh; ++k5) { const LAS unsigned char* p = lds + KS + (16 * (w + 5 * kh + k5) + li) * ROW + 8 * g * 2; ka_[k5] = *(const LAS bf16x8*)p; kb_[k5] = *(const LAS bf16x8*)(p + 64); }
;             __builtin_amdgcn_sched_barrier(0);
; #pragma unroll
;             for (int k5 = 0; k5 < 5 - kh; ++k5) { const int kt = 5 * kh + k5;
;                 f32x4 s = (f32x4){0.f, 0.f, 0.f, 0.f};
;                 s = MFMA16(ka_[k5], q0, s); s = MFMA16(kb_[k5], q1, s);
; #pragma unroll
;                 for (int r = 0; r < 4; ++r) { const int j = 4 * g + r; const int dist = 128 + li - 16 * kt - j;
;                     bool valid = (kt == 0) ? (j > li) : ((kt == 8) ? (j <= li) : true);
;                     if (nb == 0) valid = valid && (16 * (w + kt) + j >= 128);
;                     s[r] = valid ? s[r] - slope * (float)dist : -INFINITY; mx = fmaxf(mx, s[r]); }
;                 sc[kt] = s; }
;             __builtin_amdgcn_sched_barrier(0); }
	v_readlane_b32 s44, v254, 24
	v_and_b32_e32 v16, 1, v16
	v_readlane_b32 s89, v254, 43
	v_readlane_b32 s1, v253, 63
	v_readlane_b32 s3, v254, 7
	v_readlane_b32 s45, v254, 25
	v_cmp_eq_u32_e64 s[86:87], 1, v16
	v_cndmask_b32_e64 v16, 0, 1, s[88:89]
	v_readlane_b32 s88, v254, 44
	s_or_b64 s[52:53], vcc, s[0:1]
	v_readlane_b32 s0, v254, 0
	s_or_b64 s[94:95], vcc, s[2:3]
	v_readlane_b32 s2, v254, 8
	v_readlane_b32 s42, v254, 20
	s_or_b64 s[74:75], vcc, s[44:45]
	v_readlane_b32 s44, v254, 26
	v_readlane_b32 s46, v254, 47
	v_readlane_b32 s89, v254, 45
	v_readlane_b32 s1, v254, 1
	v_readlane_b32 s3, v254, 9
	v_readlane_b32 s43, v254, 21
	v_readlane_b32 s45, v254, 27
	v_readlane_b32 s47, v254, 48
	v_cndmask_b32_e64 v17, 0, 1, s[88:89]
	s_or_b64 s[16:17], vcc, s[0:1]
	v_readlane_b32 s0, v254, 2
	s_or_b64 s[96:97], vcc, s[2:3]
	v_readlane_b32 s2, v254, 10
	v_readlane_b32 s4, v254, 12
	v_readlane_b32 s10, v254, 14
	v_readlane_b32 s12, v254, 16
	v_readlane_b32 s40, v254, 18
	s_or_b64 s[72:73], vcc, s[42:43]
	v_readlane_b32 s42, v254, 22
	s_or_b64 s[76:77], vcc, s[44:45]
	v_readlane_b32 s44, v254, 28
	s_or_b64 s[78:79], vcc, s[46:47]
	v_readlane_b32 s46, v254, 49
	v_readlane_b32 s80, v254, 51
	v_cndmask_b32_e32 v16, v17, v16, vcc
	v_readlane_b32 s1, v254, 3
	v_readlane_b32 s3, v254, 11
	v_readlane_b32 s5, v254, 13
	v_readlane_b32 s11, v254, 15
	v_readlane_b32 s13, v254, 17
	v_readlane_b32 s41, v254, 19
	v_readlane_b32 s43, v254, 23
	v_readlane_b32 s45, v254, 29
	v_readlane_b32 s47, v254, 50
	v_readlane_b32 s81, v254, 52
	v_and_b32_e32 v16, 1, v16
	s_or_b64 s[0:1], vcc, s[0:1]
	s_or_b64 s[2:3], vcc, s[2:3]
	s_or_b64 s[4:5], vcc, s[4:5]
	s_or_b64 s[10:11], vcc, s[10:11]
	s_or_b64 s[12:13], vcc, s[12:13]
	s_or_b64 s[40:41], vcc, s[40:41]
	s_or_b64 s[42:43], vcc, s[42:43]
	s_or_b64 s[44:45], vcc, s[44:45]
	s_or_b64 s[46:47], vcc, s[46:47]
	s_or_b64 s[80:81], vcc, s[80:81]
	v_cmp_eq_u32_e64 s[88:89], 1, v16
.LBB0_97:
	v_readlane_b32 s37, v253, 13
	s_add_i32 s37, s37, s20
	s_nop 0
	v_cvt_f32_u32_e32 v16, s37
	s_mov_b32 s37, 0xc2fc0000
	v_mul_f32_e32 v17, 0xbe800000, v16
	v_cmp_gt_f32_e32 vcc, s37, v17
	s_nop 1
	v_cndmask_b32_e32 v17, 0, v221, vcc
	v_fmac_f32_e32 v17, 0xbe800000, v16
	v_exp_f32_e32 v16, v17
	s_and_b64 vcc, vcc, exec
	s_cselect_b32 s37, 0xffffffc0, 0
	v_ldexp_f32 v38, v16, s37
	s_add_i32 s37, s20, 1
	s_cmp_lg_u32 s20, 7
	s_cselect_b32 vcc_lo, s37, 7
	s_lshl_b32 s20, vcc_lo, 7
	s_ashr_i32 vcc_hi, vcc_lo, 31
	v_lshl_add_u64 v[20:21], v[28:29], 0, s[20:21]
	s_lshl_b64 vcc, vcc, 2
	v_readlane_b32 s20, v253, 15
	s_add_u32 vcc_lo, s20, vcc_lo
	v_readlane_b32 s20, v253, 17
	global_load_dwordx4 v[16:19], v[20:21], off nt
	s_nop 0
	global_load_dwordx4 v[20:23], v[20:21], off offset:64 nt
	s_addc_u32 vcc_hi, s20, vcc_hi
	global_load_dword v33, v1, vcc
	ds_read_b128 v[34:37], v91
	ds_read_b128 v[108:111], v91 offset:64
	ds_read_b128 v[112:115], v92
	ds_read_b128 v[116:119], v92 offset:64
	ds_read_b128 v[120:123], v93
	ds_read_b128 v[124:127], v93 offset:64
	ds_read_b128 v[128:131], v94
	ds_read_b128 v[132:135], v94 offset:64
	ds_read_b128 v[136:139], v95
	ds_read_b128 v[140:143], v95 offset:64
	s_waitcnt vmcnt(5) lgkmcnt(9)
	v_mfma_f32_16x16x32_bf16 v[34:37], v[34:37], v[12:15], 0
	v_readlane_b32 vcc_lo, v253, 18
	v_readlane_b32 vcc_hi, v253, 19
	s_waitcnt vmcnt(4) lgkmcnt(8)
	v_mfma_f32_16x16x32_bf16 v[34:37], v[108:111], v[8:11], v[34:37]
	s_waitcnt lgkmcnt(7)
	v_mfma_f32_16x16x32_bf16 v[108:111], v[112:115], v[12:15], 0
	s_nop 5
	v_fma_f32 v34, -v38, v49, v34
	v_cndmask_b32_e32 v39, v222, v34, vcc
	v_readlane_b32 vcc_lo, v254, 58
	v_fma_f32 v35, -v38, v50, v35
	v_readlane_b32 vcc_hi, v254, 59
	v_fma_f32 v36, -v38, v51, v36
	s_nop 0
	v_cndmask_b32_e32 v42, v222, v35, vcc
	v_readlane_b32 vcc_lo, v254, 60
	v_readlane_b32 vcc_hi, v254, 61
	v_fma_f32 v35, -v38, v52, v37
	s_waitcnt vmcnt(3)
	v_max3_f32 v34, v32, v39, v42
	v_cndmask_b32_e32 v43, v222, v36, vcc
	v_readlane_b32 vcc_lo, v254, 62
	v_readlane_b32 vcc_hi, v254, 63
	s_nop 1
	v_cndmask_b32_e32 v144, v222, v35, vcc
	v_max3_f32 v112, v34, v43, v144
	s_waitcnt lgkmcnt(6)
	v_mfma_f32_16x16x32_bf16 v[34:37], v[116:119], v[8:11], v[108:111]
	v_readlane_b32 vcc_lo, v255, 0
	v_readlane_b32 vcc_hi, v255, 1
	s_waitcnt lgkmcnt(5)
	v_mfma_f32_16x16x32_bf16 v[108:111], v[120:123], v[12:15], 0
	s_nop 3
	v_fma_f32 v34, -v38, v53, v34
	v_cndmask_b32_e32 v145, v222, v34, vcc
	v_readlane_b32 vcc_lo, v255, 2
	v_fma_f32 v34, -v38, v54, v35
	v_readlane_b32 vcc_hi, v255, 3
	v_fma_f32 v35, -v38, v55, v36
	s_nop 0
	v_cndmask_b32_e32 v146, v222, v34, vcc
	v_readlane_b32 vcc_lo, v255, 4
	v_readlane_b32 vcc_hi, v255, 5
	v_max3_f32 v34, v112, v145, v146
	s_nop 0
	v_cndmask_b32_e32 v147, v222, v35, vcc
	v_readlane_b32 vcc_lo, v255, 6
	v_fma_f32 v35, -v38, v56, v37
	v_readlane_b32 vcc_hi, v255, 7
	s_nop 1
	v_cndmask_b32_e32 v148, v222, v35, vcc
	v_max3_f32 v112, v34, v147, v148
	s_waitcnt lgkmcnt(4)
	v_mfma_f32_16x16x32_bf16 v[34:37], v[124:127], v[8:11], v[108:111]
	v_readlane_b32 vcc_lo, v255, 8
	v_readlane_b32 vcc_hi, v255, 9
	s_waitcnt lgkmcnt(3)
	v_mfma_f32_16x16x32_bf16 v[108:111], v[128:131], v[12:15], 0
	s_nop 3
	v_fma_f32 v34, -v38, v57, v34
	v_cndmask_b32_e32 v149, v222, v34, vcc
	v_readlane_b32 vcc_lo, v255, 10
	v_fma_f32 v34, -v38, v58, v35
	v_readlane_b32 vcc_hi, v255, 11
	v_fma_f32 v35, -v38, v59, v36
	s_nop 0
	v_cndmask_b32_e32 v150, v222, v34, vcc
	v_readlane_b32 vcc_lo, v255, 12
	v_readlane_b32 vcc_hi, v255, 13
	v_max3_f32 v34, v112, v149, v150
	s_nop 0
	v_cndmask_b32_e32 v151, v222, v35, vcc
	v_fma_f32 v35, -v38, v60, v37
	v_cndmask_b32_e64 v152, v222, v35, s[38:39]
	v_max3_f32 v112, v34, v151, v152
	s_waitcnt lgkmcnt(2)
; #define LAS __attribute__((address_space(3)))
; #define MFMA16(a, b, c) __builtin_amdgcn_mfma_f32_16x16x32_bf16((a), (b), (c), 0, 0, 0)
; __device__ __forceinline__ void attn_phase(LAS unsigned char* lds, const bf16* QKV, const float* sinks, bf16* AO, int G, int bid) {
;     ...
;             for (int k5 = 0; k5 < 5 - kh; ++k5) { const LAS unsigned char* p = lds + KS + (16 * (w + 5 * kh + k5) + li) * ROW + 8 * g * 2; ka_[k5] = *(const LAS bf16x8*)p; kb_[k5] = *(const LAS bf16x8*)(p + 64); }
;             __builtin_amdgcn_sched_barrier(0);
; #pragma unroll
;             for (int k5 = 0; k5 < 5 - kh; ++k5) { const int kt = 5 * kh + k5;
;                 f32x4 s = (f32x4){0.f, 0.f, 0.f, 0.f};
;                 s = MFMA16(ka_[k5], q0, s); s = MFMA16(kb_[k5], q1, s);
; #pragma unroll
;                 for (int r = 0; r < 4; ++r) { const int j = 4 * g + r; const int dist = 128 + li - 16 * kt - j;
;                     bool valid = (kt == 0) ? (j > li) : ((kt == 8) ? (j <= li) : true);
;                     if (nb == 0) valid = valid && (16 * (w + kt) + j >= 128);
;                     s[r] = valid ? s[r] - slope * (float)dist : -INFINITY; mx = fmaxf(mx, s[r]); }
;                 sc[kt] = s; }
;             __builtin_amdgcn_sched_barrier(0); }
;             mx = fmaxf(mx, __shfl_xor(mx, 16)); mx = fmaxf(mx, __shfl_xor(mx, 32));
;             float lsum = 0.f;
; #pragma unroll
;             for (int kt = 0; kt < 9; ++kt)
; #pragma unroll
;                 for (int r = 0; r < 4; ++r) { const float p = __expf(sc[kt][r] - mx); sc[kt][r] = p; lsum += p; }
	v_mfma_f32_16x16x32_bf16 v[34:37], v[132:135], v[8:11], v[108:111]
	s_waitcnt lgkmcnt(1)
	v_mfma_f32_16x16x32_bf16 v[108:111], v[136:139], v[12:15], 0
	s_nop 5
	v_fma_f32 v34, -v38, v61, v34
	v_cndmask_b32_e64 v153, v222, v34, s[22:23]
	v_fma_f32 v34, -v38, v62, v35
	v_fma_f32 v35, -v38, v63, v36
	v_cndmask_b32_e64 v154, v222, v34, s[52:53]
	v_cndmask_b32_e64 v155, v222, v35, s[16:17]
	v_fma_f32 v35, -v38, v64, v37
	v_max3_f32 v34, v112, v153, v154
	v_cndmask_b32_e64 v136, v222, v35, s[0:1]
	v_max3_f32 v112, v34, v155, v136
	s_waitcnt lgkmcnt(0)
	v_mfma_f32_16x16x32_bf16 v[34:37], v[140:143], v[8:11], v[108:111]
	s_nop 7
	v_fma_f32 v34, -v38, v65, v34
	v_cndmask_b32_e64 v137, v222, v34, s[92:93]
	v_fma_f32 v34, -v38, v66, v35
	v_fma_f32 v35, -v38, v67, v36
	v_cndmask_b32_e64 v138, v222, v34, s[94:95]
	v_cndmask_b32_e64 v139, v222, v35, s[96:97]
	v_fma_f32 v35, -v38, v68, v37
	v_max3_f32 v34, v112, v137, v138
	v_cndmask_b32_e64 v140, v222, v35, s[2:3]
	v_max3_f32 v141, v34, v139, v140
	ds_read_b128 v[34:37], v96
	ds_read_b128 v[108:111], v96 offset:64
	ds_read_b128 v[112:115], v97
	ds_read_b128 v[116:119], v97 offset:64
	ds_read_b128 v[120:123], v98
	ds_read_b128 v[124:127], v98 offset:64
	ds_read_b128 v[128:131], v99
	ds_read_b128 v[132:135], v99 offset:64
	s_waitcnt lgkmcnt(7)
	v_mfma_f32_16x16x32_bf16 v[34:37], v[34:37], v[12:15], 0
	s_waitcnt lgkmcnt(6)
	v_mfma_f32_16x16x32_bf16 v[34:37], v[108:111], v[8:11], v[34:37]
	s_waitcnt lgkmcnt(5)
	v_mfma_f32_16x16x32_bf16 v[108:111], v[112:115], v[12:15], 0
	s_nop 5
	v_fma_f32 v34, -v38, v69, v34
	v_fma_f32 v35, -v38, v70, v35
	v_fma_f32 v36, -v38, v71, v36
	v_cndmask_b32_e64 v142, v222, v34, s[4:5]
	v_cndmask_b32_e64 v143, v222, v35, s[10:11]
	v_fma_f32 v35, -v38, v72, v37
	v_cndmask_b32_e64 v156, v222, v36, s[12:13]
	v_max3_f32 v34, v141, v142, v143
	v_cndmask_b32_e64 v112, v222, v35, s[40:41]
	v_max3_f32 v113, v34, v156, v112
	s_waitcnt lgkmcnt(4)
	v_mfma_f32_16x16x32_bf16 v[34:37], v[116:119], v[8:11], v[108:111]
	s_waitcnt lgkmcnt(3)
	v_mfma_f32_16x16x32_bf16 v[108:111], v[120:123], v[12:15], 0
	s_waitcnt lgkmcnt(1)
	v_mfma_f32_16x16x32_bf16 v[12:15], v[128:131], v[12:15], 0
	s_nop 3
	v_fma_f32 v34, -v38, v73, v34
	v_cndmask_b32_e64 v114, v222, v34, s[72:73]
	v_fma_f32 v34, -v38, v74, v35
	v_cndmask_b32_e64 v115, v222, v34, s[42:43]
	v_fma_f32 v35, -v38, v75, v36
	v_max3_f32 v34, v113, v114, v115
	v_cndmask_b32_e64 v113, v222, v35, s[74:75]
	v_fma_f32 v35, -v38, v76, v37
	v_cndmask_b32_e64 v116, v222, v35, s[76:77]
	v_max3_f32 v117, v34, v113, v116
	v_mfma_f32_16x16x32_bf16 v[34:37], v[124:127], v[8:11], v[108:111]
	s_waitcnt lgkmcnt(0)
	v_mfma_f32_16x16x32_bf16 v[8:11], v[132:135], v[8:11], v[12:15]
	s_nop 5
	v_fma_f32 v34, -v38, v77, v34
	v_fma_f32 v35, -v38, v78, v35
	v_cndmask_b32_e64 v34, v222, v34, s[44:45]
	v_cndmask_b32_e64 v35, v222, v35, s[78:79]
	v_fma_f32 v36, -v38, v79, v36
	v_fma_f32 v37, -v38, v80, v37
	v_max3_f32 v108, v117, v34, v35
	v_cndmask_b32_e64 v36, v222, v36, s[46:47]
	v_cndmask_b32_e64 v37, v222, v37, s[80:81]
	v_fma_f32 v8, -v38, v81, v8
	v_fma_f32 v9, -v38, v82, v9
	v_max3_f32 v108, v108, v36, v37
	v_cndmask_b32_e64 v8, v222, v8, s[82:83]
	v_cndmask_b32_e64 v9, v222, v9, s[84:85]
	v_fma_f32 v10, -v38, v83, v10
	v_fma_f32 v11, -v38, v84, v11
	v_max3_f32 v12, v108, v8, v9
	v_cndmask_b32_e64 v10, v222, v10, s[86:87]
	v_cndmask_b32_e64 v11, v222, v11, s[88:89]
	v_max3_f32 v12, v12, v10, v11
	ds_bpermute_b32 v13, v30, v12
	s_waitcnt lgkmcnt(0)
	v_max_f32_e32 v13, v13, v13
	v_max_f32_e32 v12, v12, v13
	ds_bpermute_b32 v13, v31, v12
	s_waitcnt lgkmcnt(0)
	v_max_f32_e32 v13, v13, v13
	v_max_f32_e32 v12, v12, v13
	v_sub_f32_e32 v110, v149, v12
	v_mul_f32_e32 v110, 0x3fb8aa3b, v110
	v_exp_f32_e32 v117, v110
	v_sub_f32_e32 v110, v150, v12
	v_mul_f32_e32 v110, 0x3fb8aa3b, v110
	v_exp_f32_e32 v118, v110
	v_sub_f32_e32 v110, v151, v12
	v_mul_f32_e32 v110, 0x3fb8aa3b, v110
	v_exp_f32_e32 v119, v110
	v_sub_f32_e32 v110, v152, v12
	v_mul_f32_e32 v110, 0x3fb8aa3b, v110
	v_exp_f32_e32 v120, v110
	v_sub_f32_e32 v110, v153, v12
	v_mul_f32_e32 v110, 0x3fb8aa3b, v110
	v_exp_f32_e32 v121, v110
	v_sub_f32_e32 v110, v154, v12
	v_sub_f32_e32 v13, v39, v12
	v_mul_f32_e32 v110, 0x3fb8aa3b, v110
	v_mul_f32_e32 v13, 0x3fb8aa3b, v13
	v_sub_f32_e32 v15, v42, v12
	v_exp_f32_e32 v122, v110
	v_sub_f32_e32 v110, v155, v12
	v_exp_f32_e32 v13, v13
	v_mul_f32_e32 v15, 0x3fb8aa3b, v15
	v_sub_f32_e32 v38, v43, v12
	v_mul_f32_e32 v110, 0x3fb8aa3b, v110
	v_exp_f32_e32 v15, v15
	v_mul_f32_e32 v38, 0x3fb8aa3b, v38
	v_sub_f32_e32 v39, v144, v12
	v_exp_f32_e32 v123, v110
	v_sub_f32_e32 v110, v136, v12
	v_exp_f32_e32 v38, v38
	v_mul_f32_e32 v39, 0x3fb8aa3b, v39
	v_sub_f32_e32 v42, v145, v12
	v_mul_f32_e32 v110, 0x3fb8aa3b, v110
	v_exp_f32_e32 v39, v39
	v_mul_f32_e32 v42, 0x3fb8aa3b, v42
	v_sub_f32_e32 v43, v146, v12
	v_exp_f32_e32 v124, v110
	v_sub_f32_e32 v110, v137, v12
	v_add_f32_e32 v14, 0, v13
	v_exp_f32_e32 v42, v42
	v_mul_f32_e32 v43, 0x3fb8aa3b, v43
	v_sub_f32_e32 v108, v147, v12
	v_mul_f32_e32 v110, 0x3fb8aa3b, v110
	v_add_f32_e32 v14, v15, v14
	v_exp_f32_e32 v43, v43
	v_mul_f32_e32 v108, 0x3fb8aa3b, v108
	v_sub_f32_e32 v109, v148, v12
	v_exp_f32_e32 v132, v110
	v_sub_f32_e32 v110, v138, v12
	v_add_f32_e32 v14, v38, v14
	v_exp_f32_e32 v108, v108
	v_mul_f32_e32 v109, 0x3fb8aa3b, v109
	v_mul_f32_e32 v110, 0x3fb8aa3b, v110
	v_add_f32_e32 v14, v39, v14
	v_exp_f32_e32 v109, v109
	v_exp_f32_e32 v133, v110
	v_sub_f32_e32 v110, v139, v12
	v_add_f32_e32 v14, v42, v14
	v_mul_f32_e32 v110, 0x3fb8aa3b, v110
	v_add_f32_e32 v14, v43, v14
	v_exp_f32_e32 v134, v110
	v_sub_f32_e32 v110, v140, v12
; #define LAS __attribute__((address_space(3)))
; __device__ __forceinline__ s16x4 tr_read(LAS const unsigned char* p) { return __builtin_bit_cast(s16x4, __builtin_amdgcn_ds_read_tr16_b64_v4i16((LAS s16x4*)p)); }
; __device__ __forceinline__ bf16x8 cat8(s16x4 a, s16x4 b) { return (bf16x8){a[0], a[1], a[2], a[3], b[0], b[1], b[2], b[3]}; }
; __device__ __forceinline__ bf16x8 pack8(f32x4 a, f32x4 b) { v4u w; w.x = pk2(a[0], a[1]); w.y = pk2(a[2], a[3]); w.z = pk2(b[0], b[1]); w.w = pk2(b[2], b[3]); return __builtin_bit_cast(bf16x8, w); }
; #define MFMA16(a, b, c) __builtin_amdgcn_mfma_f32_16x16x32_bf16((a), (b), (c), 0, 0, 0)
; __device__ __forceinline__ void attn_phase(LAS unsigned char* lds, const bf16* QKV, const float* sinks, bf16* AO, int G, int bid) {
;     ...
;             float lsum = 0.f;
; #pragma unroll
;             for (int kt = 0; kt < 9; ++kt)
; #pragma unroll
;                 for (int r = 0; r < 4; ++r) { const float p = __expf(sc[kt][r] - mx); sc[kt][r] = p; lsum += p; }
;             sc[9] = (f32x4){0.f, 0.f, 0.f, 0.f};
;             lsum += __shfl_xor(lsum, 16); lsum += __shfl_xor(lsum, 32);
;             lsum += __expf(sink - mx);
;             const float inv = 1.0f / lsum;
;             f32x4 oa[4];
; #pragma unroll
;             for (int dt = 0; dt < 4; ++dt) oa[dt] = (f32x4){0.f, 0.f, 0.f, 0.f};
; #pragma unroll
;             for (int i = 0; i < 5; ++i) { const bf16x8 pfr = pack8(sc[2 * i], sc[2 * i + 1]); s16x4 va_[4], vb_[4];
; #pragma unroll
;                 for (int dt = 0; dt < 4; ++dt) { const LAS unsigned char* p = lds + VS + (16 * (w + 2 * i) + 4 * g + (li >> 2)) * ROW + (16 * dt + 4 * (li & 3)) * 2; va_[dt] = tr_read(p); vb_[dt] = tr_read(p + 16 * ROW); }
;                 __builtin_amdgcn_sched_barrier(0);
; #pragma unroll
;                 for (int dt = 0; dt < 4; ++dt) oa[dt] = MFMA16(cat8(va_[dt], vb_[dt]), pfr, oa[dt]);
;                 __builtin_amdgcn_sched_barrier(0); }
	v_add_f32_e32 v14, v108, v14
	v_mul_f32_e32 v110, 0x3fb8aa3b, v110
	v_add_f32_e32 v14, v109, v14
	v_exp_f32_e32 v135, v110
	v_sub_f32_e32 v110, v142, v12
	v_add_f32_e32 v14, v117, v14
	v_mul_f32_e32 v110, 0x3fb8aa3b, v110
	v_add_f32_e32 v14, v118, v14
	v_exp_f32_e32 v136, v110
	v_sub_f32_e32 v110, v143, v12
	v_add_f32_e32 v14, v119, v14
	v_mul_f32_e32 v110, 0x3fb8aa3b, v110
	v_add_f32_e32 v14, v120, v14
	v_exp_f32_e32 v137, v110
	v_sub_f32_e32 v110, v156, v12
	v_add_f32_e32 v14, v121, v14
	v_mul_f32_e32 v110, 0x3fb8aa3b, v110
	v_add_f32_e32 v14, v122, v14
	v_exp_f32_e32 v138, v110
	v_sub_f32_e32 v110, v112, v12
	v_add_f32_e32 v14, v123, v14
	v_mul_f32_e32 v110, 0x3fb8aa3b, v110
	v_add_f32_e32 v14, v124, v14
	v_exp_f32_e32 v139, v110
	v_sub_f32_e32 v110, v114, v12
	v_add_f32_e32 v14, v132, v14
	v_mul_f32_e32 v110, 0x3fb8aa3b, v110
	v_add_f32_e32 v14, v133, v14
	v_exp_f32_e32 v140, v110
	v_sub_f32_e32 v110, v115, v12
	v_add_f32_e32 v14, v134, v14
	v_mul_f32_e32 v110, 0x3fb8aa3b, v110
	v_add_f32_e32 v14, v135, v14
	v_exp_f32_e32 v141, v110
	v_sub_f32_e32 v110, v113, v12
	v_sub_f32_e32 v34, v34, v12
	v_add_f32_e32 v14, v136, v14
	v_mul_f32_e32 v110, 0x3fb8aa3b, v110
	v_mul_f32_e32 v34, 0x3fb8aa3b, v34
	v_add_f32_e32 v14, v137, v14
	v_exp_f32_e32 v142, v110
	v_sub_f32_e32 v110, v116, v12
	v_exp_f32_e32 v144, v34
	v_sub_f32_e32 v34, v35, v12
	v_add_f32_e32 v14, v138, v14
	v_mul_f32_e32 v110, 0x3fb8aa3b, v110
	v_mul_f32_e32 v34, 0x3fb8aa3b, v34
	v_add_f32_e32 v14, v139, v14
	v_exp_f32_e32 v143, v110
	v_exp_f32_e32 v145, v34
	v_sub_f32_e32 v34, v36, v12
	v_add_f32_e32 v14, v140, v14
	v_mul_f32_e32 v34, 0x3fb8aa3b, v34
	v_add_f32_e32 v14, v141, v14
	v_exp_f32_e32 v146, v34
	v_sub_f32_e32 v34, v37, v12
	v_sub_f32_e32 v9, v9, v12
	v_add_f32_e32 v14, v142, v14
	v_mul_f32_e32 v34, 0x3fb8aa3b, v34
	v_sub_f32_e32 v8, v8, v12
	v_mul_f32_e32 v9, 0x3fb8aa3b, v9
	v_add_f32_e32 v14, v143, v14
	v_exp_f32_e32 v147, v34
	v_mul_f32_e32 v8, 0x3fb8aa3b, v8
	v_exp_f32_e32 v149, v9
	v_sub_f32_e32 v9, v10, v12
	v_add_f32_e32 v14, v144, v14
	v_exp_f32_e32 v148, v8
	v_mul_f32_e32 v9, 0x3fb8aa3b, v9
	v_add_f32_e32 v14, v145, v14
	v_exp_f32_e32 v150, v9
	v_sub_f32_e32 v9, v11, v12
	v_add_f32_e32 v14, v146, v14
	v_mul_f32_e32 v9, 0x3fb8aa3b, v9
	v_add_f32_e32 v14, v147, v14
	v_exp_f32_e32 v151, v9
	v_add_f32_e32 v8, v148, v14
	v_add_f32_e32 v8, v149, v8
	v_add_f32_e32 v8, v150, v8
	v_add_f32_e32 v8, v151, v8
	ds_bpermute_b32 v9, v30, v8
	s_waitcnt lgkmcnt(0)
	v_add_f32_e32 v8, v8, v9
	ds_bpermute_b32 v9, v31, v8
	s_waitcnt lgkmcnt(0)
	v_add_f32_e32 v8, v8, v9
	v_sub_f32_e32 v9, v32, v12
	v_mul_f32_e32 v9, 0x3fb8aa3b, v9
	v_exp_f32_e32 v9, v9
	s_nop 0
	v_add_f32_e32 v32, v9, v8
	v_cvt_pk_bf16_f32 v8, v13, v15
	v_cvt_pk_bf16_f32 v9, v38, v39
	v_cvt_pk_bf16_f32 v10, v42, v43
	v_cvt_pk_bf16_f32 v11, v108, v109
	ds_read_b64_tr_b16 v[14:15], v100 offset:41472
	ds_read_b64_tr_b16 v[12:13], v100 offset:39168
	ds_read_b64_tr_b16 v[34:35], v100 offset:39200
	ds_read_b64_tr_b16 v[36:37], v100 offset:41504
	ds_read_b64_tr_b16 v[108:109], v100 offset:39232
	ds_read_b64_tr_b16 v[110:111], v100 offset:41536
	ds_read_b64_tr_b16 v[112:113], v100 offset:39264
	ds_read_b64_tr_b16 v[114:115], v100 offset:41568
	s_waitcnt lgkmcnt(6)
	v_mfma_f32_16x16x32_bf16 v[12:15], v[12:15], v[8:11], 0
	s_waitcnt lgkmcnt(4)
	v_mfma_f32_16x16x32_bf16 v[34:37], v[34:37], v[8:11], 0
	s_waitcnt lgkmcnt(2)
	v_mfma_f32_16x16x32_bf16 v[108:111], v[108:111], v[8:11], 0
	s_waitcnt lgkmcnt(0)
	v_mfma_f32_16x16x32_bf16 v[8:11], v[112:115], v[8:11], 0
	v_cvt_pk_bf16_f32 v112, v117, v118
	v_cvt_pk_bf16_f32 v113, v119, v120
	v_cvt_pk_bf16_f32 v114, v121, v122
	v_cvt_pk_bf16_f32 v115, v123, v124
	ds_read_b64_tr_b16 v[116:117], v101 offset:39168
	ds_read_b64_tr_b16 v[120:121], v101 offset:39200
	ds_read_b64_tr_b16 v[124:125], v101 offset:39232
	ds_read_b64_tr_b16 v[128:129], v101 offset:39264
	ds_read_b64_tr_b16 v[118:119], v101 offset:41472
	ds_read_b64_tr_b16 v[122:123], v101 offset:41504
	ds_read_b64_tr_b16 v[126:127], v101 offset:41536
	ds_read_b64_tr_b16 v[130:131], v101 offset:41568
	s_waitcnt lgkmcnt(3)
	v_mfma_f32_16x16x32_bf16 v[12:15], v[116:119], v[112:115], v[12:15]
	s_waitcnt lgkmcnt(0)
; #define LAS __attribute__((address_space(3)))
; #define LBAR() do { asm volatile("s_waitcnt lgkmcnt(0)" ::: "memory"); __builtin_amdgcn_s_barrier(); asm volatile("" ::: "memory"); } while (0)
; __device__ __forceinline__ unsigned pk2(float lo, float hi) { return pg8::cvt_pk_bf16(lo, hi); }
; __device__ __forceinline__ s16x4 tr_read(LAS const unsigned char* p) { return __builtin_bit_cast(s16x4, __builtin_amdgcn_ds_read_tr16_b64_v4i16((LAS s16x4*)p)); }
; __device__ __forceinline__ bf16x8 cat8(s16x4 a, s16x4 b) { return (bf16x8){a[0], a[1], a[2], a[3], b[0], b[1], b[2], b[3]}; }
; __device__ __forceinline__ bf16x8 pack8(f32x4 a, f32x4 b) { v4u w; w.x = pk2(a[0], a[1]); w.y = pk2(a[2], a[3]); w.z = pk2(b[0], b[1]); w.w = pk2(b[2], b[3]); return __builtin_bit_cast(bf16x8, w); }
; #define MFMA16(a, b, c) __builtin_amdgcn_mfma_f32_16x16x32_bf16((a), (b), (c), 0, 0, 0)
; __device__ __forceinline__ void attn_phase(LAS unsigned char* lds, const bf16* QKV, const float* sinks, bf16* AO, int G, int bid) {
;     ...
;             for (int i = 0; i < 5; ++i) { const bf16x8 pfr = pack8(sc[2 * i], sc[2 * i + 1]); s16x4 va_[4], vb_[4];
; #pragma unroll
;                 for (int dt = 0; dt < 4; ++dt) { const LAS unsigned char* p = lds + VS + (16 * (w + 2 * i) + 4 * g + (li >> 2)) * ROW + (16 * dt + 4 * (li & 3)) * 2; va_[dt] = tr_read(p); vb_[dt] = tr_read(p + 16 * ROW); }
;                 __builtin_amdgcn_sched_barrier(0);
; #pragma unroll
;                 for (int dt = 0; dt < 4; ++dt) oa[dt] = MFMA16(cat8(va_[dt], vb_[dt]), pfr, oa[dt]);
;                 __builtin_amdgcn_sched_barrier(0); }
;             LAS unsigned char* stg = lds + 2 * 272 * ROW + w * 2304;
; #pragma unroll
;             for (int dt = 0; dt < 4; ++dt) { v2u o; o.x = pk2(oa[dt][0] * inv, oa[dt][1] * inv); o.y = pk2(oa[dt][2] * inv, oa[dt][3] * inv); *(LAS v2u*)(stg + li * 144 + dt * 32 + g * 8) = o; }
; #pragma unroll
;             for (int i = 0; i < 2; ++i) { const int row = (lane >> 3) + 8 * i; const v4u x = *(const LAS v4u*)(stg + row * 144 + (lane & 7) * 16);
;                 *(v4u*)(AO + (size_t)(nb * 128 + 16 * w + row) * DM + hq * 64 + (lane & 7) * 8) = x; }
;         }
;         LBAR();
;     }
; }
	v_mfma_f32_16x16x32_bf16 v[8:11], v[128:131], v[112:115], v[8:11]
	v_mfma_f32_16x16x32_bf16 v[34:37], v[120:123], v[112:115], v[34:37]
	v_mfma_f32_16x16x32_bf16 v[108:111], v[124:127], v[112:115], v[108:111]
	v_cvt_pk_bf16_f32 v112, v132, v133
	v_cvt_pk_bf16_f32 v113, v134, v135
	v_cvt_pk_bf16_f32 v114, v136, v137
	v_cvt_pk_bf16_f32 v115, v138, v139
	ds_read_b64_tr_b16 v[116:117], v102 offset:39168
	ds_read_b64_tr_b16 v[120:121], v102 offset:39200
	ds_read_b64_tr_b16 v[124:125], v102 offset:39232
	ds_read_b64_tr_b16 v[128:129], v102 offset:39264
	ds_read_b64_tr_b16 v[118:119], v102 offset:41472
	ds_read_b64_tr_b16 v[122:123], v102 offset:41504
	ds_read_b64_tr_b16 v[126:127], v102 offset:41536
	ds_read_b64_tr_b16 v[130:131], v102 offset:41568
	s_waitcnt lgkmcnt(3)
	v_mfma_f32_16x16x32_bf16 v[12:15], v[116:119], v[112:115], v[12:15]
	s_waitcnt lgkmcnt(0)
	v_mfma_f32_16x16x32_bf16 v[8:11], v[128:131], v[112:115], v[8:11]
	v_mfma_f32_16x16x32_bf16 v[34:37], v[120:123], v[112:115], v[34:37]
	v_mfma_f32_16x16x32_bf16 v[108:111], v[124:127], v[112:115], v[108:111]
	v_cvt_pk_bf16_f32 v112, v140, v141
	v_cvt_pk_bf16_f32 v113, v142, v143
	v_cvt_pk_bf16_f32 v114, v144, v145
	v_cvt_pk_bf16_f32 v115, v146, v147
	ds_read_b64_tr_b16 v[116:117], v103 offset:39168
	ds_read_b64_tr_b16 v[120:121], v103 offset:39200
	ds_read_b64_tr_b16 v[124:125], v103 offset:39232
	ds_read_b64_tr_b16 v[128:129], v103 offset:39264
	ds_read_b64_tr_b16 v[118:119], v103 offset:41472
	ds_read_b64_tr_b16 v[122:123], v103 offset:41504
	ds_read_b64_tr_b16 v[126:127], v103 offset:41536
	ds_read_b64_tr_b16 v[130:131], v103 offset:41568
	s_waitcnt lgkmcnt(3)
	v_mfma_f32_16x16x32_bf16 v[12:15], v[116:119], v[112:115], v[12:15]
	s_waitcnt lgkmcnt(0)
	v_mfma_f32_16x16x32_bf16 v[8:11], v[128:131], v[112:115], v[8:11]
	v_mfma_f32_16x16x32_bf16 v[34:37], v[120:123], v[112:115], v[34:37]
	v_mfma_f32_16x16x32_bf16 v[108:111], v[124:127], v[112:115], v[108:111]
	v_cvt_pk_bf16_f32 v112, v148, v149
	v_cvt_pk_bf16_f32 v113, v150, v151
	v_cvt_pk_bf16_f32 v114, v1, v1
	v_cvt_pk_bf16_f32 v115, v1, v1
	ds_read_b64_tr_b16 v[116:117], v104 offset:39168
	ds_read_b64_tr_b16 v[120:121], v104 offset:39200
	ds_read_b64_tr_b16 v[124:125], v104 offset:39232
	ds_read_b64_tr_b16 v[128:129], v104 offset:39264
	ds_read_b64_tr_b16 v[118:119], v104 offset:41472
	ds_read_b64_tr_b16 v[122:123], v104 offset:41504
	ds_read_b64_tr_b16 v[126:127], v104 offset:41536
	ds_read_b64_tr_b16 v[130:131], v104 offset:41568
	s_waitcnt lgkmcnt(3)
	v_mfma_f32_16x16x32_bf16 v[12:15], v[116:119], v[112:115], v[12:15]
	s_waitcnt lgkmcnt(0)
	v_mfma_f32_16x16x32_bf16 v[8:11], v[128:131], v[112:115], v[8:11]
	v_mfma_f32_16x16x32_bf16 v[34:37], v[120:123], v[112:115], v[34:37]
	v_mfma_f32_16x16x32_bf16 v[108:111], v[124:127], v[112:115], v[108:111]
	v_div_scale_f32 v38, vcc, v32, v32, 1.0
	v_rcp_f32_e32 v39, v38
	s_cmp_eq_u32 s37, 8
	s_mov_b32 s20, s37
	v_fma_f32 v42, -v38, v39, 1.0
	v_fmac_f32_e32 v39, v42, v39
	v_div_scale_f32 v42, vcc, 1.0, v32, 1.0
	v_mul_f32_e32 v43, v42, v39
	v_fma_f32 v112, -v38, v43, v42
	v_fmac_f32_e32 v43, v112, v39
	v_fma_f32 v38, -v38, v43, v42
	v_div_fmas_f32 v38, v38, v39, v43
	v_div_fixup_f32 v32, v38, v32, 1.0
	v_mul_f32_e32 v12, v32, v12
	v_mul_f32_e32 v13, v32, v13
	v_cvt_pk_bf16_f32 v12, v12, v13
	v_mul_f32_e32 v13, v32, v14
	v_mul_f32_e32 v14, v32, v15
	v_cvt_pk_bf16_f32 v13, v13, v14
	ds_write_b64 v105, v[12:13]
	v_mul_f32_e32 v12, v32, v34
	v_mul_f32_e32 v13, v32, v35
	v_cvt_pk_bf16_f32 v12, v12, v13
	v_mul_f32_e32 v13, v32, v36
	v_mul_f32_e32 v14, v32, v37
	v_cvt_pk_bf16_f32 v13, v13, v14
	ds_write_b64 v105, v[12:13] offset:32
	v_mul_f32_e32 v12, v32, v108
	v_mul_f32_e32 v13, v32, v109
	v_cvt_pk_bf16_f32 v12, v12, v13
	v_mul_f32_e32 v13, v32, v110
	v_mul_f32_e32 v8, v32, v8
	v_mul_f32_e32 v9, v32, v9
	v_mul_f32_e32 v14, v32, v111
	v_cvt_pk_bf16_f32 v13, v13, v14
	ds_write_b64 v105, v[12:13] offset:64
	v_cvt_pk_bf16_f32 v8, v8, v9
	v_mul_f32_e32 v9, v32, v10
	v_mul_f32_e32 v10, v32, v11
	v_cvt_pk_bf16_f32 v9, v9, v10
	ds_write_b64 v105, v[8:9] offset:96
	ds_read_b128 v[8:11], v106
	s_waitcnt vmcnt(2)
	v_mov_b64_e32 v[12:13], v[16:17]
	s_waitcnt vmcnt(0)
	v_mov_b32_e32 v32, v33
	v_mov_b64_e32 v[14:15], v[18:19]
	s_waitcnt lgkmcnt(0)
	global_store_dwordx4 v[24:25], v[8:11], off nt
	ds_read_b128 v[8:11], v107
	v_lshl_add_u64 v[24:25], v[24:25], 0, s[24:25]
	s_waitcnt lgkmcnt(0)
	global_store_dwordx4 v[26:27], v[8:11], off nt
	s_nop 1
	v_mov_b64_e32 v[8:9], v[20:21]
	v_lshl_add_u64 v[26:27], v[26:27], 0, s[24:25]
	v_mov_b64_e32 v[10:11], v[22:23]
	s_cbranch_scc0 .LBB0_97
	s_waitcnt lgkmcnt(0)
	s_barrier
	v_readlane_b32 s17, v254, 57
	v_readlane_b32 s0, v251, 54
	v_readlane_b32 s16, v254, 55
	v_readlane_b32 s13, v254, 56
	s_add_i32 s17, s17, s90
	s_add_i32 s16, s16, s0
	s_add_i32 s13, s13, s90
	v_readlane_b32 s40, v254, 53
	s_cmpk_gt_i32 s17, 0xff
	s_movk_i32 s37, 0x2000
	v_readlane_b32 s41, v254, 54
	s_cbranch_scc0 .LBB0_86
